# v51: + convert_uv rows software-pipelined (next row's 8 loads prefetched before the current row's quantisation)
# speedup vs baseline: 1.1501x; 1.0017x over previous
; __device__ void convert_uv(const Params& p, int part, int nparts) {
;     ...
;   for (int row = blockIdx.x * 8 + wid + part * (int)gridDim.x * 8; row < 32768; row += nparts * (int)gridDim.x * 8) {
;     const bool isv = row >= 16384;
;     const int e = row & 16383;
;     const float* src = (isv ? p.peer_v : p.peer_u) + (size_t)e * DM + lane * 32;
;     float vals[32];
;     float ss = 0.f;
; #pragma unroll
;     for (int q = 0; q < 8; ++q) {
;       f32x4 t = *(const f32x4*)(src + q * 4);
;       if (!isv) t *= *(const f32x4*)(p.norm_ffn_w + lane * 32 + q * 4);
.LBB0_1109:
	s_mul_i32 s0, s48, s96
	s_add_i32 s0, s0, s2
	v_lshl_add_u32 v38, s0, 3, v164
	v_cmp_gt_i32_e32 vcc, s59, v38
	s_and_saveexec_b64 s[10:11], vcc
	s_cbranch_execz .LBB0_1084
	v_ashrrev_i32_e32 v79, 31, v78
	v_lshlrev_b64 v[2:3], 10, v[78:79]
	v_lshl_add_u64 v[34:35], v[78:79], 2, s[18:19]
	v_lshl_add_u64 v[36:37], v[82:83], 0, v[2:3]
	s_mov_b64 s[46:47], 0
	v_mov_b32_e32 v39, v75
	global_load_dwordx4 v[168:171], v[76:77], off
	global_load_dwordx4 v[172:175], v[76:77], off offset:16
	global_load_dwordx4 v[176:179], v[76:77], off offset:32
	global_load_dwordx4 v[180:183], v[76:77], off offset:48
	global_load_dwordx4 v[184:187], v[76:77], off offset:64
	global_load_dwordx4 v[188:191], v[76:77], off offset:80
	global_load_dwordx4 v[192:195], v[76:77], off offset:96
	global_load_dwordx4 v[196:199], v[76:77], off offset:112
	v_mov_b32_e32 v89, v63
	v_cmp_lt_i32_e64 s[70:71], s62, v38
	v_mov_b32_e32 v234, s24
	v_mov_b32_e32 v236, s26
	v_mov_b32_e32 v235, s25
	v_mov_b32_e32 v237, s27
	v_cndmask_b32_e64 v234, v234, v236, s[70:71]
	v_cndmask_b32_e64 v235, v235, v237, s[70:71]
	v_and_b32_e32 v236, 0x1fff800, v39
	v_lshlrev_b32_e32 v236, 2, v236
	v_mov_b32_e32 v237, 0
	v_lshl_add_u64 v[234:235], v[234:235], 0, v[236:237]
	v_lshl_add_u64 v[234:235], v[234:235], 0, v[88:89]
	global_load_dwordx4 v[200:203], v[234:235], off
	global_load_dwordx4 v[204:207], v[234:235], off offset:16
	global_load_dwordx4 v[208:211], v[234:235], off offset:32
	global_load_dwordx4 v[212:215], v[234:235], off offset:48
	global_load_dwordx4 v[216:219], v[234:235], off offset:64
	global_load_dwordx4 v[220:223], v[234:235], off offset:80
	global_load_dwordx4 v[224:227], v[234:235], off offset:96
	global_load_dwordx4 v[228:231], v[234:235], off offset:112
	s_waitcnt vmcnt(0)
	s_branch .LBB0_1112

; __device__ void convert_uv(const Params& p, int part, int nparts) {
;     ...
;   for (int row = blockIdx.x * 8 + wid + part * (int)gridDim.x * 8; row < 32768; row += nparts * (int)gridDim.x * 8) {
;     const bool isv = row >= 16384;
;     const int e = row & 16383;
;     const float* src = (isv ? p.peer_v : p.peer_u) + (size_t)e * DM + lane * 32;
;     float vals[32];
;     float ss = 0.f;
; #pragma unroll
;     for (int q = 0; q < 8; ++q) {
;       f32x4 t = *(const f32x4*)(src + q * 4);
;       if (!isv) t *= *(const f32x4*)(p.norm_ffn_w + lane * 32 + q * 4);
; #pragma unroll
;       for (int k = 0; k < 4; ++k) {
;         vals[q * 4 + k] = t[k];
;         ss += t[k] * t[k];
;       }
;     }
;     ss = wave_sum(ss);
;     const float rms = sqrtf(ss * (1.f / 2048.f));
;     const float sc = rms * (2.6f / 7.f);
;     const float inv = sc > 0.f ? 1.f / sc : 0.f;
.LBB0_1112:
	s_waitcnt vmcnt(2) lgkmcnt(0)
	v_mov_b64 v[26:27], v[200:201]
	v_mov_b64 v[28:29], v[202:203]
	v_mov_b64 v[30:31], v[204:205]
	v_mov_b64 v[32:33], v[206:207]
	v_mov_b64 v[18:19], v[208:209]
	v_mov_b64 v[20:21], v[210:211]
	v_mov_b64 v[22:23], v[212:213]
	v_mov_b64 v[24:25], v[214:215]
	v_mov_b64 v[10:11], v[216:217]
	v_mov_b64 v[12:13], v[218:219]
	v_mov_b64 v[14:15], v[220:221]
	v_mov_b64 v[16:17], v[222:223]
	v_mov_b64 v[2:3], v[224:225]
	v_mov_b64 v[4:5], v[226:227]
	v_mov_b64 v[6:7], v[228:229]
	v_mov_b64 v[8:9], v[230:231]
	v_cmp_lt_i32_e64 s[8:9], s62, v38
	v_cmp_gt_i32_e32 vcc, s53, v38
	v_add_u32_e32 v232, v38, v74
	v_add_u32_e32 v233, v39, v116
	v_cmp_ge_i32_e64 s[12:13], s66, v232
	v_cmp_lt_i32_e64 s[70:71], s62, v232
	v_mov_b32_e32 v234, s24
	v_mov_b32_e32 v236, s26
	v_mov_b32_e32 v235, s25
	v_mov_b32_e32 v237, s27
	v_cndmask_b32_e64 v234, v234, v236, s[70:71]
	v_cndmask_b32_e64 v235, v235, v237, s[70:71]
	v_and_b32_e32 v236, 0x1fff800, v233
	v_lshlrev_b32_e32 v236, 2, v236
	v_mov_b32_e32 v237, 0
	v_lshl_add_u64 v[234:235], v[234:235], 0, v[236:237]
	v_lshl_add_u64 v[234:235], v[234:235], 0, v[88:89]
	s_and_saveexec_b64 s[16:17], s[12:13]
	global_load_dwordx4 v[200:203], v[234:235], off
	global_load_dwordx4 v[204:207], v[234:235], off offset:16
	global_load_dwordx4 v[208:211], v[234:235], off offset:32
	global_load_dwordx4 v[212:215], v[234:235], off offset:48
	global_load_dwordx4 v[216:219], v[234:235], off offset:64
	global_load_dwordx4 v[220:223], v[234:235], off offset:80
	global_load_dwordx4 v[224:227], v[234:235], off offset:96
	global_load_dwordx4 v[228:231], v[234:235], off offset:112
	s_mov_b64 exec, s[16:17]
	s_and_saveexec_b64 s[0:1], vcc
	s_cbranch_execz .LBB0_1121
	v_pk_mul_f32 v[26:27], v[26:27], v[168:169]
	v_pk_mul_f32 v[28:29], v[28:29], v[170:171]
	v_pk_mul_f32 v[30:31], v[30:31], v[172:173]
	v_pk_mul_f32 v[32:33], v[32:33], v[174:175]
	v_pk_mul_f32 v[18:19], v[18:19], v[176:177]
	v_pk_mul_f32 v[20:21], v[20:21], v[178:179]
	v_pk_mul_f32 v[22:23], v[22:23], v[180:181]
	v_pk_mul_f32 v[24:25], v[24:25], v[182:183]
	v_pk_mul_f32 v[10:11], v[10:11], v[184:185]
	v_pk_mul_f32 v[12:13], v[12:13], v[186:187]
	v_pk_mul_f32 v[14:15], v[14:15], v[188:189]
	v_pk_mul_f32 v[16:17], v[16:17], v[190:191]
	v_pk_mul_f32 v[2:3], v[2:3], v[192:193]
	v_pk_mul_f32 v[4:5], v[4:5], v[194:195]
	v_pk_mul_f32 v[6:7], v[6:7], v[196:197]
	v_pk_mul_f32 v[8:9], v[8:9], v[198:199]
.LBB0_1121:
	s_or_b64 exec, exec, s[0:1]
	v_mul_f32_e32 v44, v27, v27
	v_fmac_f32_e32 v44, v26, v26
	v_fmac_f32_e32 v44, v28, v28
	v_fmac_f32_e32 v44, v29, v29
	v_fmac_f32_e32 v44, v30, v30
	v_fmac_f32_e32 v44, v31, v31
	v_fmac_f32_e32 v44, v32, v32
	v_fmac_f32_e32 v44, v33, v33
	v_fmac_f32_e32 v44, v18, v18
	v_fmac_f32_e32 v44, v19, v19
	v_fmac_f32_e32 v44, v20, v20
	v_fmac_f32_e32 v44, v21, v21
	v_fmac_f32_e32 v44, v22, v22
	v_fmac_f32_e32 v44, v23, v23
	v_fmac_f32_e32 v44, v24, v24
	v_fmac_f32_e32 v44, v25, v25
	v_fmac_f32_e32 v44, v10, v10
	v_fmac_f32_e32 v44, v11, v11
	v_fmac_f32_e32 v44, v12, v12
	v_fmac_f32_e32 v44, v13, v13
	v_fmac_f32_e32 v44, v14, v14
	v_fmac_f32_e32 v44, v15, v15
	v_fmac_f32_e32 v44, v16, v16
	v_fmac_f32_e32 v44, v17, v17
	v_fmac_f32_e32 v44, v2, v2
	v_fmac_f32_e32 v44, v3, v3
	v_fmac_f32_e32 v44, v4, v4
	v_fmac_f32_e32 v44, v5, v5
	v_pk_mul_f32 v[42:43], v[6:7], v[6:7]
	v_pk_mul_f32 v[40:41], v[8:9], v[8:9]
	v_add_f32_e32 v42, v44, v42
	v_add_f32_e32 v42, v43, v42
	v_add_f32_e32 v40, v40, v42
	v_add_f32_e32 v40, v41, v40
	ds_bpermute_b32 v41, v106, v40
	s_waitcnt lgkmcnt(0)
	v_add_f32_e32 v40, v40, v41
	ds_bpermute_b32 v41, v107, v40
	s_waitcnt lgkmcnt(0)
	v_add_f32_e32 v40, v40, v41
	ds_bpermute_b32 v41, v108, v40
	s_waitcnt lgkmcnt(0)
	v_add_f32_e32 v40, v40, v41
	ds_bpermute_b32 v41, v109, v40
	s_waitcnt lgkmcnt(0)
	v_add_f32_e32 v40, v40, v41
	ds_bpermute_b32 v41, v110, v40
	s_waitcnt lgkmcnt(0)
	v_add_f32_e32 v40, v40, v41
	ds_bpermute_b32 v41, v111, v40
	s_waitcnt lgkmcnt(0)
	v_add_f32_e32 v40, v40, v41
	v_mul_f32_e32 v40, 0x3a000000, v40
	v_mul_f32_e32 v41, 0x4f800000, v40
	v_cmp_gt_f32_e32 vcc, s63, v40
	s_nop 1
	v_cndmask_b32_e32 v40, v40, v41, vcc
	v_sqrt_f32_e32 v41, v40
	s_nop 0
	v_add_u32_e32 v42, -1, v41
	v_add_u32_e32 v43, 1, v41
	v_fma_f32 v44, -v42, v41, v40
	v_fma_f32 v45, -v43, v41, v40
	v_cmp_ge_f32_e64 s[0:1], 0, v44
	s_nop 1
	v_cndmask_b32_e64 v41, v41, v42, s[0:1]
	v_cmp_lt_f32_e64 s[0:1], 0, v45
	s_nop 1
	v_cndmask_b32_e64 v41, v41, v43, s[0:1]
	v_mul_f32_e32 v42, 0x37800000, v41
	v_cndmask_b32_e32 v41, v41, v42, vcc
	v_cmp_class_f32_e32 vcc, v40, v119
	s_nop 1
	v_cndmask_b32_e32 v40, v41, v40, vcc
	v_mul_f32_e32 v40, 0x3ebe2be2, v40
	v_div_scale_f32 v41, s[0:1], v40, v40, 1.0
	v_rcp_f32_e32 v42, v41
	v_div_scale_f32 v43, vcc, 1.0, v40, 1.0
	v_fma_f32 v44, -v41, v42, 1.0
	v_fmac_f32_e32 v42, v44, v42
	v_mul_f32_e32 v44, v43, v42
	v_fma_f32 v45, -v41, v44, v43
	v_fmac_f32_e32 v44, v45, v42
	v_fma_f32 v41, -v41, v44, v43
	v_div_fmas_f32 v41, v41, v42, v44
	v_div_fixup_f32 v41, v41, v40, 1.0
	v_cmp_lt_f32_e32 vcc, 0, v40
	s_nop 1
	v_cndmask_b32_e32 v41, 0, v41, vcc
	v_mul_f32_e32 v26, v26, v41
	v_rndne_f32_e32 v26, v26
	v_mul_f32_e32 v28, v28, v41
	v_med3_f32 v26, v26, s64, v120
	v_rndne_f32_e32 v28, v28
	v_mul_f32_e32 v32, v32, v41
	v_mul_f32_e32 v27, v27, v41
	v_mul_f32_e32 v31, v31, v41
	v_cvt_i32_f32_e32 v26, v26
	v_med3_f32 v28, v28, s64, v120
	v_rndne_f32_e32 v32, v32
	v_rndne_f32_e32 v27, v27
	v_rndne_f32_e32 v31, v31
	v_cvt_i32_f32_e32 v28, v28
	v_med3_f32 v32, v32, s64, v120
	v_med3_f32 v27, v27, s64, v120
	v_med3_f32 v31, v31, s64, v120
	v_cvt_i32_f32_e32 v32, v32
	v_cvt_i32_f32_e32 v27, v27
; __device__ void convert_uv(const Params& p, int part, int nparts) {
;     ...
;     u32x4 o;
; #pragma unroll
;     for (int m = 0; m < 4; ++m) {
;       unsigned w = 0;
; #pragma unroll
;       for (int j = 0; j < 4; ++j) {
;         const float lo = fminf(fmaxf(rintf(vals[m * 8 + j] * inv), -7.f), 7.f);
;         const float hi = fminf(fmaxf(rintf(vals[m * 8 + 4 + j] * inv), -7.f), 7.f);
;         const unsigned bl = isv ? (unsigned)((int)lo + 8) : ((unsigned)(int)lo & 0xfu);
;         const unsigned bh = isv ? (unsigned)((int)hi + 8) : ((unsigned)(int)hi & 0xfu);
;         w |= (bl | (bh << 4)) << (8 * j);
;       }
;       o[m] = w;
	v_cvt_i32_f32_e32 v31, v31
	v_mul_f32_e32 v18, v18, v41
	v_add_u32_e32 v42, 8, v26
	v_and_b32_e32 v26, 15, v26
	v_rndne_f32_e32 v18, v18
	v_mul_f32_e32 v22, v22, v41
	v_cndmask_b32_e64 v26, v26, v42, s[8:9]
	v_add_u32_e32 v42, 8, v28
	v_and_b32_e32 v28, 15, v28
	v_med3_f32 v18, v18, s64, v120
	v_rndne_f32_e32 v22, v22
	v_mul_f32_e32 v19, v19, v41
	v_cndmask_b32_e64 v28, v28, v42, s[8:9]
	v_add_u32_e32 v42, 8, v32
	v_and_b32_e32 v32, 15, v32
	v_cvt_i32_f32_e32 v18, v18
	v_med3_f32 v22, v22, s64, v120
	v_rndne_f32_e32 v19, v19
	v_mul_f32_e32 v23, v23, v41
	v_add_u32_e32 v44, 8, v27
	v_and_b32_e32 v27, 15, v27
	v_add_u32_e32 v45, 8, v31
	v_and_b32_e32 v31, 15, v31
	v_cndmask_b32_e64 v32, v32, v42, s[8:9]
	v_cvt_i32_f32_e32 v22, v22
	v_med3_f32 v19, v19, s64, v120
	v_rndne_f32_e32 v23, v23
	v_mul_f32_e32 v20, v20, v41
	v_cndmask_b32_e64 v27, v27, v44, s[8:9]
	v_cndmask_b32_e64 v31, v31, v45, s[8:9]
	v_lshlrev_b32_e32 v32, 20, v32
	v_lshlrev_b32_e32 v28, 16, v28
	v_cvt_i32_f32_e32 v19, v19
	v_med3_f32 v23, v23, s64, v120
	v_rndne_f32_e32 v20, v20
	v_mul_f32_e32 v24, v24, v41
	v_lshlrev_b32_e32 v31, 12, v31
	v_lshlrev_b32_e32 v27, 8, v27
	v_or3_b32 v26, v28, v26, v32
	v_cvt_i32_f32_e32 v23, v23
	v_med3_f32 v20, v20, s64, v120
	v_rndne_f32_e32 v24, v24
	v_mul_f32_e32 v21, v21, v41
	v_mul_f32_e32 v25, v25, v41
	v_or3_b32 v26, v26, v27, v31
	v_add_u32_e32 v27, 8, v18
	v_and_b32_e32 v18, 15, v18
	v_cvt_i32_f32_e32 v20, v20
	v_med3_f32 v24, v24, s64, v120
	v_rndne_f32_e32 v21, v21
	v_rndne_f32_e32 v25, v25
	v_cndmask_b32_e64 v18, v18, v27, s[8:9]
	v_add_u32_e32 v27, 8, v22
	v_and_b32_e32 v22, 15, v22
	v_cvt_i32_f32_e32 v24, v24
	v_med3_f32 v21, v21, s64, v120
	v_med3_f32 v25, v25, s64, v120
	v_cndmask_b32_e64 v22, v22, v27, s[8:9]
	v_add_u32_e32 v27, 8, v19
	v_and_b32_e32 v19, 15, v19
	v_cvt_i32_f32_e32 v21, v21
	v_cvt_i32_f32_e32 v25, v25
	v_cndmask_b32_e64 v19, v19, v27, s[8:9]
	v_add_u32_e32 v27, 8, v23
	v_and_b32_e32 v23, 15, v23
	v_mul_f32_e32 v10, v10, v41
	v_cndmask_b32_e64 v23, v23, v27, s[8:9]
	v_add_u32_e32 v27, 8, v20
	v_and_b32_e32 v20, 15, v20
	v_rndne_f32_e32 v10, v10
	v_mul_f32_e32 v14, v14, v41
	v_cndmask_b32_e64 v20, v20, v27, s[8:9]
	v_add_u32_e32 v27, 8, v24
	v_and_b32_e32 v24, 15, v24
	v_med3_f32 v10, v10, s64, v120
	v_rndne_f32_e32 v14, v14
	v_mul_f32_e32 v11, v11, v41
	v_cndmask_b32_e64 v24, v24, v27, s[8:9]
	v_add_u32_e32 v27, 8, v21
	v_lshlrev_b32_e32 v25, 4, v25
	v_cvt_i32_f32_e32 v10, v10
	v_med3_f32 v14, v14, s64, v120
	v_rndne_f32_e32 v11, v11
	v_mul_f32_e32 v15, v15, v41
	v_lshlrev_b32_e32 v24, 20, v24
	v_lshlrev_b32_e32 v20, 16, v20
	v_bitop3_b32 v27, v25, v27, s65 bitop3:0xde
	v_and_or_b32 v21, v21, 15, v25
	v_cvt_i32_f32_e32 v14, v14
	v_med3_f32 v11, v11, s64, v120
	v_rndne_f32_e32 v15, v15
	v_mul_f32_e32 v12, v12, v41
	v_lshlrev_b32_e32 v23, 12, v23
	v_lshlrev_b32_e32 v19, 8, v19
	v_cndmask_b32_e64 v21, v21, v27, s[8:9]
	v_or3_b32 v18, v20, v18, v24
	v_cvt_i32_f32_e32 v11, v11
	v_med3_f32 v15, v15, s64, v120
	v_rndne_f32_e32 v12, v12
	v_mul_f32_e32 v16, v16, v41
	v_lshlrev_b32_e32 v22, 4, v22
	v_lshlrev_b32_e32 v21, 24, v21
	v_or3_b32 v18, v18, v19, v23
	v_cvt_i32_f32_e32 v15, v15
	v_med3_f32 v12, v12, s64, v120
	v_rndne_f32_e32 v16, v16
	v_mul_f32_e32 v13, v13, v41
	v_mul_f32_e32 v17, v17, v41
	v_or3_b32 v27, v18, v22, v21
	v_add_u32_e32 v18, 8, v10
	v_and_b32_e32 v10, 15, v10
	v_cvt_i32_f32_e32 v12, v12
	v_med3_f32 v16, v16, s64, v120
	v_rndne_f32_e32 v13, v13
	v_rndne_f32_e32 v17, v17
	v_cndmask_b32_e64 v10, v10, v18, s[8:9]
	v_add_u32_e32 v18, 8, v14
	v_and_b32_e32 v14, 15, v14
	v_cvt_i32_f32_e32 v16, v16
	v_med3_f32 v13, v13, s64, v120
	v_med3_f32 v17, v17, s64, v120
; __device__ void convert_uv(const Params& p, int part, int nparts) {
;     ...
;     for (int m = 0; m < 4; ++m) {
;       unsigned w = 0;
; #pragma unroll
;       for (int j = 0; j < 4; ++j) {
;         const float lo = fminf(fmaxf(rintf(vals[m * 8 + j] * inv), -7.f), 7.f);
;         const float hi = fminf(fmaxf(rintf(vals[m * 8 + 4 + j] * inv), -7.f), 7.f);
;         const unsigned bl = isv ? (unsigned)((int)lo + 8) : ((unsigned)(int)lo & 0xfu);
;         const unsigned bh = isv ? (unsigned)((int)hi + 8) : ((unsigned)(int)hi & 0xfu);
;         w |= (bl | (bh << 4)) << (8 * j);
;       }
;       o[m] = w;
;     }
;     *(u32x4*)(tb + (size_t)row * 1024 + lane * 16) = o;
;     if (lane == 0) scales[row] = sc;
	v_cndmask_b32_e64 v14, v14, v18, s[8:9]
	v_add_u32_e32 v18, 8, v11
	v_and_b32_e32 v11, 15, v11
	v_cvt_i32_f32_e32 v13, v13
	v_cvt_i32_f32_e32 v17, v17
	v_cndmask_b32_e64 v11, v11, v18, s[8:9]
	v_add_u32_e32 v18, 8, v15
	v_and_b32_e32 v15, 15, v15
	v_mul_f32_e32 v2, v2, v41
	v_cndmask_b32_e64 v15, v15, v18, s[8:9]
	v_add_u32_e32 v18, 8, v12
	v_and_b32_e32 v12, 15, v12
	v_rndne_f32_e32 v2, v2
	v_mul_f32_e32 v6, v6, v41
	v_cndmask_b32_e64 v12, v12, v18, s[8:9]
	v_add_u32_e32 v18, 8, v16
	v_and_b32_e32 v16, 15, v16
	v_med3_f32 v2, v2, s64, v120
	v_rndne_f32_e32 v6, v6
	v_mul_f32_e32 v3, v3, v41
	v_cndmask_b32_e64 v16, v16, v18, s[8:9]
	v_add_u32_e32 v18, 8, v13
	v_lshlrev_b32_e32 v17, 4, v17
	v_cvt_i32_f32_e32 v2, v2
	v_med3_f32 v6, v6, s64, v120
	v_rndne_f32_e32 v3, v3
	v_mul_f32_e32 v7, v7, v41
	v_lshlrev_b32_e32 v16, 20, v16
	v_lshlrev_b32_e32 v12, 16, v12
	v_bitop3_b32 v18, v17, v18, s65 bitop3:0xde
	v_and_or_b32 v13, v13, 15, v17
	v_cvt_i32_f32_e32 v6, v6
	v_med3_f32 v3, v3, s64, v120
	v_rndne_f32_e32 v7, v7
	v_mul_f32_e32 v4, v4, v41
	v_lshlrev_b32_e32 v15, 12, v15
	v_lshlrev_b32_e32 v11, 8, v11
	v_cndmask_b32_e64 v13, v13, v18, s[8:9]
	v_or3_b32 v10, v12, v10, v16
	v_cvt_i32_f32_e32 v3, v3
	v_med3_f32 v7, v7, s64, v120
	v_rndne_f32_e32 v4, v4
	v_mul_f32_e32 v8, v8, v41
	v_mul_f32_e32 v29, v29, v41
	v_mul_f32_e32 v33, v33, v41
	v_lshlrev_b32_e32 v14, 4, v14
	v_lshlrev_b32_e32 v13, 24, v13
	v_or3_b32 v10, v10, v11, v15
	v_cvt_i32_f32_e32 v7, v7
	v_med3_f32 v4, v4, s64, v120
	v_rndne_f32_e32 v8, v8
	v_mul_f32_e32 v30, v30, v41
	v_rndne_f32_e32 v29, v29
	v_rndne_f32_e32 v33, v33
	v_or3_b32 v28, v10, v14, v13
	v_add_u32_e32 v10, 8, v2
	v_and_b32_e32 v2, 15, v2
	v_cvt_i32_f32_e32 v4, v4
	v_med3_f32 v8, v8, s64, v120
	v_mul_f32_e32 v5, v5, v41
	v_mul_f32_e32 v9, v9, v41
	v_rndne_f32_e32 v30, v30
	v_med3_f32 v29, v29, s64, v120
	v_med3_f32 v33, v33, s64, v120
	v_cndmask_b32_e64 v2, v2, v10, s[8:9]
	v_add_u32_e32 v10, 8, v6
	v_and_b32_e32 v6, 15, v6
	v_cvt_i32_f32_e32 v8, v8
	v_rndne_f32_e32 v5, v5
	v_rndne_f32_e32 v9, v9
	v_med3_f32 v30, v30, s64, v120
	v_cvt_i32_f32_e32 v29, v29
	v_cvt_i32_f32_e32 v33, v33
	v_cndmask_b32_e64 v6, v6, v10, s[8:9]
	v_add_u32_e32 v10, 8, v3
	v_and_b32_e32 v3, 15, v3
	v_med3_f32 v5, v5, s64, v120
	v_med3_f32 v9, v9, s64, v120
	v_cvt_i32_f32_e32 v30, v30
	v_cndmask_b32_e64 v3, v3, v10, s[8:9]
	v_add_u32_e32 v10, 8, v7
	v_and_b32_e32 v7, 15, v7
	v_cvt_i32_f32_e32 v5, v5
	v_cvt_i32_f32_e32 v9, v9
	v_cndmask_b32_e64 v7, v7, v10, s[8:9]
	v_add_u32_e32 v10, 8, v4
	v_and_b32_e32 v4, 15, v4
	v_cndmask_b32_e64 v4, v4, v10, s[8:9]
	v_add_u32_e32 v10, 8, v8
	v_and_b32_e32 v8, 15, v8
	v_add_u32_e32 v42, 8, v29
	v_lshlrev_b32_e32 v33, 4, v33
	v_cndmask_b32_e64 v8, v8, v10, s[8:9]
	v_add_u32_e32 v43, 8, v30
	v_and_b32_e32 v30, 15, v30
	v_bitop3_b32 v42, v33, v42, s65 bitop3:0xde
	v_and_or_b32 v29, v29, 15, v33
	v_lshlrev_b32_e32 v8, 20, v8
	v_lshlrev_b32_e32 v4, 16, v4
	v_add_u32_e32 v10, 8, v5
	v_lshlrev_b32_e32 v9, 4, v9
	v_cndmask_b32_e64 v30, v30, v43, s[8:9]
	v_cndmask_b32_e64 v29, v29, v42, s[8:9]
	v_lshlrev_b32_e32 v7, 12, v7
	v_lshlrev_b32_e32 v3, 8, v3
	v_bitop3_b32 v10, v9, v10, s65 bitop3:0xde
	v_and_or_b32 v5, v5, 15, v9
	s_mov_b64 vcc, s[8:9]
	v_or3_b32 v2, v4, v2, v8
	v_lshlrev_b32_e32 v30, 4, v30
	v_lshlrev_b32_e32 v29, 24, v29
	v_lshlrev_b32_e32 v6, 4, v6
	v_cndmask_b32_sdwa v5, v5, v10, vcc dst_sel:BYTE_3 dst_unused:UNUSED_PAD src0_sel:DWORD src1_sel:DWORD
	v_or3_b32 v2, v2, v3, v7
	v_or3_b32 v26, v26, v30, v29
	v_or3_b32 v29, v2, v6, v5
	global_store_dwordx4 v[36:37], v[26:29], off
	s_and_saveexec_b64 s[0:1], s[6:7]
	s_cbranch_execz .LBB0_1111
	global_store_dword v[34:35], v40, off
	s_branch .LBB0_1111
